# P1b K-loop: XN (A operand) LDS-DMA loads with nt
# baseline (speedup 1.0000x reference)
.LBB0_306:
	ds_read_b128 v[112:115], v213
	ds_read_b128 v[116:119], v213 offset:1024
	ds_read_b128 v[136:139], v213 offset:2048
	ds_read_b128 v[140:143], v213 offset:3072
	ds_read_b128 v[144:147], v243
	ds_read_b128 v[148:151], v243 offset:1024
	ds_read_b128 v[152:155], v243 offset:2048
	ds_read_b128 v[156:159], v243 offset:3072
	s_add_u32 s17, s8, 0xfffc0080
	s_addc_u32 s26, s9, -1
	s_cmp_eq_u32 s16, 12
	s_cselect_b32 s73, s11, s26
	s_cselect_b32 s72, s87, s17
	s_cselect_b32 s41, s89, vcc_hi
	s_cselect_b32 s40, s95, vcc_lo
	v_lshl_add_u64 v[192:193], s[8:9], 0, v[220:221]
	s_add_i32 m0, s55, 0xc000
	ds_read_b128 v[160:163], v244
	ds_read_b128 v[164:167], v244 offset:1024
	ds_read_b128 v[168:171], v244 offset:2048
	ds_read_b128 v[172:175], v244 offset:3072
	ds_read_b128 v[176:179], v244 offset:4096
	ds_read_b128 v[180:183], v244 offset:5120
	ds_read_b128 v[184:187], v244 offset:6144
	ds_read_b128 v[188:191], v244 offset:7168
	global_load_lds_dwordx4 v[192:193], off nt
	v_lshl_add_u64 v[192:193], s[8:9], 0, v[222:223]
	s_add_i32 m0, s55, 0xe000
	s_nop 0
	global_load_lds_dwordx4 v[192:193], off nt
	s_waitcnt vmcnt(8)
	s_waitcnt lgkmcnt(0)
	s_barrier
	s_setprio 1
	s_waitcnt lgkmcnt(0)
	v_mfma_f32_16x16x32_bf16 v[132:135], v[112:115], v[160:163], v[132:135]
	v_mfma_f32_16x16x32_bf16 v[124:127], v[136:139], v[160:163], v[124:127]
	v_mfma_f32_16x16x32_bf16 v[108:111], v[112:115], v[168:171], v[108:111]
	v_mfma_f32_16x16x32_bf16 v[100:103], v[136:139], v[168:171], v[100:103]
	v_mfma_f32_16x16x32_bf16 v[92:95], v[112:115], v[176:179], v[92:95]
	v_mfma_f32_16x16x32_bf16 v[84:87], v[136:139], v[176:179], v[84:87]
	v_mfma_f32_16x16x32_bf16 v[76:79], v[112:115], v[184:187], v[76:79]
	v_mfma_f32_16x16x32_bf16 v[68:71], v[136:139], v[184:187], v[68:71]
	v_mfma_f32_16x16x32_bf16 v[132:135], v[116:119], v[164:167], v[132:135]
	v_mfma_f32_16x16x32_bf16 v[124:127], v[140:143], v[164:167], v[124:127]
	v_mfma_f32_16x16x32_bf16 v[108:111], v[116:119], v[172:175], v[108:111]
	v_mfma_f32_16x16x32_bf16 v[100:103], v[140:143], v[172:175], v[100:103]
	v_mfma_f32_16x16x32_bf16 v[92:95], v[116:119], v[180:183], v[92:95]
	v_mfma_f32_16x16x32_bf16 v[84:87], v[140:143], v[180:183], v[84:87]
	v_mfma_f32_16x16x32_bf16 v[76:79], v[116:119], v[188:191], v[76:79]
	v_mfma_f32_16x16x32_bf16 v[68:71], v[140:143], v[188:191], v[68:71]
	s_setprio 0
	s_setprio 1
	v_mfma_f32_16x16x32_bf16 v[128:131], v[144:147], v[160:163], v[128:131]
	v_mfma_f32_16x16x32_bf16 v[120:123], v[152:155], v[160:163], v[120:123]
	v_mfma_f32_16x16x32_bf16 v[104:107], v[144:147], v[168:171], v[104:107]
	v_mfma_f32_16x16x32_bf16 v[96:99], v[152:155], v[168:171], v[96:99]
	v_mfma_f32_16x16x32_bf16 v[88:91], v[144:147], v[176:179], v[88:91]
	v_mfma_f32_16x16x32_bf16 v[80:83], v[152:155], v[176:179], v[80:83]
	v_mfma_f32_16x16x32_bf16 v[72:75], v[144:147], v[184:187], v[72:75]
	v_mfma_f32_16x16x32_bf16 v[64:67], v[152:155], v[184:187], v[64:67]
	v_mfma_f32_16x16x32_bf16 v[128:131], v[148:151], v[164:167], v[128:131]
	v_mfma_f32_16x16x32_bf16 v[120:123], v[156:159], v[164:167], v[120:123]
	v_mfma_f32_16x16x32_bf16 v[104:107], v[148:151], v[172:175], v[104:107]
	v_mfma_f32_16x16x32_bf16 v[96:99], v[156:159], v[172:175], v[96:99]
	v_mfma_f32_16x16x32_bf16 v[88:91], v[148:151], v[180:183], v[88:91]
	v_mfma_f32_16x16x32_bf16 v[80:83], v[156:159], v[180:183], v[80:83]
	v_mfma_f32_16x16x32_bf16 v[72:75], v[148:151], v[188:191], v[72:75]
	v_mfma_f32_16x16x32_bf16 v[64:67], v[156:159], v[188:191], v[64:67]
	s_setprio 0
	s_barrier
	s_add_i32 s17, s3, s53
	v_lshl_add_u64 v[192:193], s[40:41], 0, v[204:205]
	s_mov_b32 m0, s17
	ds_read_b128 v[160:163], v244 offset:16384
	ds_read_b128 v[164:167], v244 offset:17408
	ds_read_b128 v[168:171], v244 offset:18432
	ds_read_b128 v[172:175], v244 offset:19456
	ds_read_b128 v[176:179], v244 offset:20480
	ds_read_b128 v[180:183], v244 offset:21504
	ds_read_b128 v[184:187], v244 offset:22528
	ds_read_b128 v[188:191], v244 offset:23552
	global_load_lds_dwordx4 v[192:193], off
	s_add_i32 m0, s17, 0x2000
	s_add_u32 s26, s40, 0x40000
	v_lshl_add_u64 v[194:195], s[40:41], 0, v[208:209]
	s_addc_u32 s27, s41, 0
	s_add_i32 s17, s33, s53
	global_load_lds_dwordx4 v[194:195], off
	v_lshl_add_u64 v[196:197], s[26:27], 0, v[204:205]
	s_mov_b32 m0, s17
	v_lshl_add_u64 v[198:199], s[72:73], 0, v[206:207]
	global_load_lds_dwordx4 v[196:197], off
	v_lshl_add_u64 v[196:197], s[26:27], 0, v[208:209]
	s_add_i32 m0, s17, 0x2000
	s_nop 0
	global_load_lds_dwordx4 v[196:197], off
	v_lshl_add_u64 v[196:197], s[72:73], 0, v[202:203]
	s_mov_b32 m0, s55
	s_nop 0
	global_load_lds_dwordx4 v[196:197], off nt
	s_mov_b32 m0, s63
	s_nop 0
	global_load_lds_dwordx4 v[198:199], off nt
	s_waitcnt vmcnt(8)
	s_waitcnt lgkmcnt(0)
	s_barrier
	s_setprio 1
	s_waitcnt lgkmcnt(0)
	v_mfma_f32_16x16x32_bf16 v[60:63], v[112:115], v[160:163], v[60:63]
	v_mfma_f32_16x16x32_bf16 v[52:55], v[136:139], v[160:163], v[52:55]
	v_mfma_f32_16x16x32_bf16 v[44:47], v[112:115], v[168:171], v[44:47]
	v_mfma_f32_16x16x32_bf16 v[36:39], v[136:139], v[168:171], v[36:39]
	v_mfma_f32_16x16x32_bf16 v[28:31], v[112:115], v[176:179], v[28:31]
	v_mfma_f32_16x16x32_bf16 v[20:23], v[136:139], v[176:179], v[20:23]
	v_mfma_f32_16x16x32_bf16 v[12:15], v[112:115], v[184:187], v[12:15]
	v_mfma_f32_16x16x32_bf16 v[4:7], v[136:139], v[184:187], v[4:7]
	v_mfma_f32_16x16x32_bf16 v[60:63], v[116:119], v[164:167], v[60:63]
	v_mfma_f32_16x16x32_bf16 v[52:55], v[140:143], v[164:167], v[52:55]
	v_mfma_f32_16x16x32_bf16 v[44:47], v[116:119], v[172:175], v[44:47]
	v_mfma_f32_16x16x32_bf16 v[36:39], v[140:143], v[172:175], v[36:39]
	v_mfma_f32_16x16x32_bf16 v[28:31], v[116:119], v[180:183], v[28:31]
	v_mfma_f32_16x16x32_bf16 v[20:23], v[140:143], v[180:183], v[20:23]
	v_mfma_f32_16x16x32_bf16 v[12:15], v[116:119], v[188:191], v[12:15]
	v_mfma_f32_16x16x32_bf16 v[4:7], v[140:143], v[188:191], v[4:7]
	s_setprio 0
	s_setprio 1
	v_mfma_f32_16x16x32_bf16 v[56:59], v[144:147], v[160:163], v[56:59]
	v_mfma_f32_16x16x32_bf16 v[48:51], v[152:155], v[160:163], v[48:51]
	v_mfma_f32_16x16x32_bf16 v[40:43], v[144:147], v[168:171], v[40:43]
	v_mfma_f32_16x16x32_bf16 v[32:35], v[152:155], v[168:171], v[32:35]
	v_mfma_f32_16x16x32_bf16 v[24:27], v[144:147], v[176:179], v[24:27]
	v_mfma_f32_16x16x32_bf16 v[16:19], v[152:155], v[176:179], v[16:19]
	v_mfma_f32_16x16x32_bf16 v[8:11], v[144:147], v[184:187], v[8:11]
	v_mfma_f32_16x16x32_bf16 v[0:3], v[152:155], v[184:187], v[0:3]
	v_mfma_f32_16x16x32_bf16 v[56:59], v[148:151], v[164:167], v[56:59]
	v_mfma_f32_16x16x32_bf16 v[48:51], v[156:159], v[164:167], v[48:51]
	v_mfma_f32_16x16x32_bf16 v[40:43], v[148:151], v[172:175], v[40:43]
	v_mfma_f32_16x16x32_bf16 v[32:35], v[156:159], v[172:175], v[32:35]
	v_mfma_f32_16x16x32_bf16 v[24:27], v[148:151], v[180:183], v[24:27]
	v_mfma_f32_16x16x32_bf16 v[16:19], v[156:159], v[180:183], v[16:19]
	v_mfma_f32_16x16x32_bf16 v[8:11], v[148:151], v[188:191], v[8:11]
	v_mfma_f32_16x16x32_bf16 v[0:3], v[156:159], v[188:191], v[0:3]
	s_setprio 0
	s_barrier
	s_add_i32 s17, 0, 0x18000
	s_add_i32 s28, 0, 0x1c000
	v_add_u32_e32 v140, s17, v235
	v_add_u32_e32 v156, s28, v235
	ds_read_b128 v[112:115], v140
	ds_read_b128 v[116:119], v140 offset:1024
	ds_read_b128 v[136:139], v140 offset:2048
	ds_read_b128 v[140:143], v140 offset:3072
	ds_read_b128 v[144:147], v156
	ds_read_b128 v[148:151], v156 offset:1024
	ds_read_b128 v[152:155], v156 offset:2048
	ds_read_b128 v[156:159], v156 offset:3072
	s_add_u32 s26, s72, 0x40000
	s_addc_u32 s27, s73, 0
	s_mov_b32 m0, s74
	v_lshl_add_u64 v[228:229], s[26:27], 0, v[202:203]
	ds_read_b128 v[160:163], v244 offset:32768
	ds_read_b128 v[164:167], v244 offset:33792
	ds_read_b128 v[168:171], v244 offset:34816
	ds_read_b128 v[172:175], v244 offset:35840
	ds_read_b128 v[176:179], v244 offset:36864
	ds_read_b128 v[180:183], v244 offset:37888
	ds_read_b128 v[184:187], v244 offset:38912
	ds_read_b128 v[188:191], v244 offset:39936
	global_load_lds_dwordx4 v[228:229], off nt
	v_lshl_add_u64 v[228:229], s[26:27], 0, v[206:207]
	s_mov_b32 m0, s76
	s_nop 0
	global_load_lds_dwordx4 v[228:229], off nt
	s_waitcnt vmcnt(8)
	s_waitcnt lgkmcnt(0)
	s_barrier
	s_setprio 1
	s_waitcnt lgkmcnt(0)
	v_mfma_f32_16x16x32_bf16 v[132:135], v[112:115], v[160:163], v[132:135]
	v_mfma_f32_16x16x32_bf16 v[124:127], v[136:139], v[160:163], v[124:127]
	v_mfma_f32_16x16x32_bf16 v[108:111], v[112:115], v[168:171], v[108:111]
	v_mfma_f32_16x16x32_bf16 v[100:103], v[136:139], v[168:171], v[100:103]
	v_mfma_f32_16x16x32_bf16 v[92:95], v[112:115], v[176:179], v[92:95]
	v_mfma_f32_16x16x32_bf16 v[84:87], v[136:139], v[176:179], v[84:87]
	v_mfma_f32_16x16x32_bf16 v[76:79], v[112:115], v[184:187], v[76:79]
	v_mfma_f32_16x16x32_bf16 v[68:71], v[136:139], v[184:187], v[68:71]
	v_mfma_f32_16x16x32_bf16 v[132:135], v[116:119], v[164:167], v[132:135]
	v_mfma_f32_16x16x32_bf16 v[124:127], v[140:143], v[164:167], v[124:127]
	v_mfma_f32_16x16x32_bf16 v[108:111], v[116:119], v[172:175], v[108:111]
	v_mfma_f32_16x16x32_bf16 v[100:103], v[140:143], v[172:175], v[100:103]
	v_mfma_f32_16x16x32_bf16 v[92:95], v[116:119], v[180:183], v[92:95]
	v_mfma_f32_16x16x32_bf16 v[84:87], v[140:143], v[180:183], v[84:87]
	v_mfma_f32_16x16x32_bf16 v[76:79], v[116:119], v[188:191], v[76:79]
	v_mfma_f32_16x16x32_bf16 v[68:71], v[140:143], v[188:191], v[68:71]
	s_setprio 0
	s_setprio 1
	v_mfma_f32_16x16x32_bf16 v[128:131], v[144:147], v[160:163], v[128:131]
	v_mfma_f32_16x16x32_bf16 v[120:123], v[152:155], v[160:163], v[120:123]
	v_mfma_f32_16x16x32_bf16 v[104:107], v[144:147], v[168:171], v[104:107]
	v_mfma_f32_16x16x32_bf16 v[96:99], v[152:155], v[168:171], v[96:99]
	v_mfma_f32_16x16x32_bf16 v[88:91], v[144:147], v[176:179], v[88:91]
	v_mfma_f32_16x16x32_bf16 v[80:83], v[152:155], v[176:179], v[80:83]
	v_mfma_f32_16x16x32_bf16 v[72:75], v[144:147], v[184:187], v[72:75]
	v_mfma_f32_16x16x32_bf16 v[64:67], v[152:155], v[184:187], v[64:67]
	v_mfma_f32_16x16x32_bf16 v[128:131], v[148:151], v[164:167], v[128:131]
	v_mfma_f32_16x16x32_bf16 v[120:123], v[156:159], v[164:167], v[120:123]
	v_mfma_f32_16x16x32_bf16 v[104:107], v[148:151], v[172:175], v[104:107]
	v_mfma_f32_16x16x32_bf16 v[96:99], v[156:159], v[172:175], v[96:99]
	v_mfma_f32_16x16x32_bf16 v[88:91], v[148:151], v[180:183], v[88:91]
	v_mfma_f32_16x16x32_bf16 v[80:83], v[156:159], v[180:183], v[80:83]
	v_mfma_f32_16x16x32_bf16 v[72:75], v[148:151], v[188:191], v[72:75]
	v_mfma_f32_16x16x32_bf16 v[64:67], v[156:159], v[188:191], v[64:67]
	s_setprio 0
	s_barrier
	s_add_i32 s17, s17, s53
	v_lshl_add_u64 v[192:193], v[192:193], 0, s[20:21]
	s_mov_b32 m0, s17
	ds_read_b128 v[160:163], v244 offset:49152
	ds_read_b128 v[164:167], v244 offset:50176
	ds_read_b128 v[168:171], v244 offset:51200
	ds_read_b128 v[172:175], v244 offset:52224
	ds_read_b128 v[176:179], v244 offset:53248
	ds_read_b128 v[180:183], v244 offset:54272
	ds_read_b128 v[184:187], v244 offset:55296
	ds_read_b128 v[188:191], v244 offset:56320
	global_load_lds_dwordx4 v[192:193], off
	s_add_i32 m0, s17, 0x2000
	s_add_u32 s26, s40, 0x40080
	v_lshl_add_u64 v[192:193], v[194:195], 0, s[20:21]
	s_addc_u32 s27, s41, 0
	s_add_i32 s17, s28, s53
	global_load_lds_dwordx4 v[192:193], off
	v_lshl_add_u64 v[192:193], s[26:27], 0, v[204:205]
	s_mov_b32 m0, s17
	s_nop 0
	global_load_lds_dwordx4 v[192:193], off
	v_lshl_add_u64 v[192:193], s[26:27], 0, v[208:209]
	s_add_i32 m0, s17, 0x2000
	s_nop 0
	global_load_lds_dwordx4 v[192:193], off
	v_lshl_add_u64 v[192:193], v[196:197], 0, s[20:21]
	s_mov_b32 m0, s78
	s_nop 0
	global_load_lds_dwordx4 v[192:193], off nt
	v_lshl_add_u64 v[192:193], v[198:199], 0, s[20:21]
	s_mov_b32 m0, s79
	s_nop 0
	global_load_lds_dwordx4 v[192:193], off nt
	s_waitcnt vmcnt(8)
	s_waitcnt lgkmcnt(0)
	s_barrier
	s_setprio 1
	s_waitcnt lgkmcnt(0)
	v_mfma_f32_16x16x32_bf16 v[60:63], v[112:115], v[160:163], v[60:63]
	v_mfma_f32_16x16x32_bf16 v[52:55], v[136:139], v[160:163], v[52:55]
	v_mfma_f32_16x16x32_bf16 v[44:47], v[112:115], v[168:171], v[44:47]
	v_mfma_f32_16x16x32_bf16 v[36:39], v[136:139], v[168:171], v[36:39]
	v_mfma_f32_16x16x32_bf16 v[28:31], v[112:115], v[176:179], v[28:31]
	v_mfma_f32_16x16x32_bf16 v[20:23], v[136:139], v[176:179], v[20:23]
	v_mfma_f32_16x16x32_bf16 v[12:15], v[112:115], v[184:187], v[12:15]
	v_mfma_f32_16x16x32_bf16 v[4:7], v[136:139], v[184:187], v[4:7]
	v_mfma_f32_16x16x32_bf16 v[60:63], v[116:119], v[164:167], v[60:63]
	v_mfma_f32_16x16x32_bf16 v[52:55], v[140:143], v[164:167], v[52:55]
	v_mfma_f32_16x16x32_bf16 v[44:47], v[116:119], v[172:175], v[44:47]
	v_mfma_f32_16x16x32_bf16 v[36:39], v[140:143], v[172:175], v[36:39]
	v_mfma_f32_16x16x32_bf16 v[28:31], v[116:119], v[180:183], v[28:31]
	v_mfma_f32_16x16x32_bf16 v[20:23], v[140:143], v[180:183], v[20:23]
	v_mfma_f32_16x16x32_bf16 v[12:15], v[116:119], v[188:191], v[12:15]
	v_mfma_f32_16x16x32_bf16 v[4:7], v[140:143], v[188:191], v[4:7]
	s_setprio 0
	s_setprio 1
	v_mfma_f32_16x16x32_bf16 v[56:59], v[144:147], v[160:163], v[56:59]
	v_mfma_f32_16x16x32_bf16 v[48:51], v[152:155], v[160:163], v[48:51]
	v_mfma_f32_16x16x32_bf16 v[40:43], v[144:147], v[168:171], v[40:43]
	v_mfma_f32_16x16x32_bf16 v[32:35], v[152:155], v[168:171], v[32:35]
	v_mfma_f32_16x16x32_bf16 v[24:27], v[144:147], v[176:179], v[24:27]
	v_mfma_f32_16x16x32_bf16 v[16:19], v[152:155], v[176:179], v[16:19]
	v_mfma_f32_16x16x32_bf16 v[8:11], v[144:147], v[184:187], v[8:11]
	v_mfma_f32_16x16x32_bf16 v[0:3], v[152:155], v[184:187], v[0:3]
	v_mfma_f32_16x16x32_bf16 v[56:59], v[148:151], v[164:167], v[56:59]
	v_mfma_f32_16x16x32_bf16 v[48:51], v[156:159], v[164:167], v[48:51]
	v_mfma_f32_16x16x32_bf16 v[40:43], v[148:151], v[172:175], v[40:43]
	v_mfma_f32_16x16x32_bf16 v[32:35], v[156:159], v[172:175], v[32:35]
	v_mfma_f32_16x16x32_bf16 v[24:27], v[148:151], v[180:183], v[24:27]
	v_mfma_f32_16x16x32_bf16 v[16:19], v[156:159], v[180:183], v[16:19]
	v_mfma_f32_16x16x32_bf16 v[8:11], v[148:151], v[188:191], v[8:11]
	v_mfma_f32_16x16x32_bf16 v[0:3], v[156:159], v[188:191], v[0:3]
	s_setprio 0
	s_barrier
	s_add_i32 s16, s16, 2
	s_add_u32 s8, s8, 0x100
	s_addc_u32 s9, s9, 0
	s_add_u32 vcc_lo, vcc_lo, 0x100
	s_addc_u32 vcc_hi, vcc_hi, 0
	s_cmp_gt_u32 s16, 13
	s_cbranch_scc0 .LBB0_306
	s_and_b64 vcc, exec, s[22:23]
	s_cbranch_vccnz .LBB0_311
	s_lshl_b32 s87, s10, 7
	s_cmp_gt_i32 s10, 7
	s_mov_b64 s[8:9], -1
	s_cbranch_scc1 .LBB0_312
